# stack3 + the six hot loop headers (4 GEMM K-loops, fox and diff attention steady loops) aligned to 64 bytes with s_nop padding
# speedup vs baseline: 1.0162x; 1.0029x over previous
; template <class Epi, class Sched, bool ALIGN_EPI = false, bool SP2 = false>
; __device__ __forceinline__ void gemm_phase(PG8_LAS unsigned char* lds, const Gemm g, const Sched& S, const Epi& E, const int tid_in) {
;     ...
;         float rsv[8]; E.pre(cur, wr, fr, rsv);
;         const bool has_next = S.next(ui + 1, nxt);
;         const char* nA = has_next ? (const char*)g.A + (size_t)nxt.pm * tstep : cA; const char* nB = has_next ? (const char*)g.Bt + (size_t)nxt.pn * tstep : cB;
;         for (int t = 0; t < nt; t += 2) {
;             const bool last = (t == nt - 2);
;             const char* a1 = cA + (size_t)(t + 1) * kstep;
;             const char* a2 = last ? nA : cA + (size_t)(t + 2) * kstep; const char* b2 = last ? nB : cB + (size_t)(t + 2) * kstep;
;             const char* a3 = a2 + kstep; const char* b3 = b2 + kstep;
;             if (last && has_next) S.a_ready(nxt);
;     ...
; #pragma unroll
;         for (int a = 0; a < 2; ++a)
; #pragma unroll
;             for (int b = 0; b < 2; ++b)
; #pragma unroll
;                 for (int m = 0; m < 4; ++m)
; #pragma unroll
;                     for (int n = 0; n < 2; ++n) acc[a][b][m][n] = (f32x4){0.f, 0.f, 0.f, 0.f};
;         cur = nxt; cA = nA; cB = nB; ++ui;
.LBB0_91:
	s_ashr_i32 s11, s10, 31
	s_lshl_b64 s[42:43], s[10:11], 19
	s_add_u32 s72, s1, s42
	s_addc_u32 s73, s2, s43
	s_and_b64 s[42:43], s[4:5], exec
	s_cselect_b32 s11, s73, s7
	s_cselect_b32 s42, s72, s6
	s_ashr_i32 s71, s70, 31
	s_lshl_b64 s[58:59], s[70:71], 19
	s_add_u32 s74, s3, s58
	s_addc_u32 s75, s20, s59
	s_and_b64 s[58:59], s[4:5], exec
	s_cselect_b32 s43, s75, s79
	s_cselect_b32 s58, s74, s78
	s_add_u32 s6, s6, 0x40080
	s_addc_u32 s7, s7, 0
	s_add_u32 s59, s78, 0x100
	v_mov_b32_e32 v2, 0
	s_addc_u32 s60, s79, 0
	s_mov_b32 s61, -2
	v_mov_b32_e32 v3, v2
	v_mov_b64_e32 v[4:5], 0
	v_mov_b64_e32 v[6:7], 0
	v_mov_b64_e32 v[8:9], 0
	v_mov_b64_e32 v[18:19], 0
	v_mov_b64_e32 v[20:21], 0
	v_mov_b64_e32 v[22:23], 0
	v_mov_b64_e32 v[24:25], 0
	v_mov_b64_e32 v[34:35], 0
	v_mov_b64_e32 v[36:37], 0
	v_mov_b64_e32 v[38:39], 0
	v_mov_b64_e32 v[40:41], 0
	v_mov_b64_e32 v[50:51], 0
	v_mov_b64_e32 v[52:53], 0
	v_mov_b64_e32 v[54:55], 0
	v_mov_b64_e32 v[56:57], 0
	v_mov_b64_e32 v[10:11], 0
	s_waitcnt lgkmcnt(0)
	v_mov_b64_e32 v[12:13], 0
	v_mov_b64_e32 v[14:15], 0
	v_mov_b64_e32 v[16:17], 0
	v_mov_b64_e32 v[26:27], 0
	v_mov_b64_e32 v[28:29], 0
	v_mov_b64_e32 v[30:31], 0
	v_mov_b64_e32 v[32:33], 0
	v_mov_b64_e32 v[42:43], 0
	v_mov_b64_e32 v[44:45], 0
	v_mov_b64_e32 v[46:47], 0
	v_mov_b64_e32 v[48:49], 0
	v_mov_b64_e32 v[58:59], 0
	v_mov_b64_e32 v[60:61], 0
	v_mov_b64_e32 v[62:63], 0
	v_mov_b64_e32 v[64:65], 0
	v_mov_b64_e32 v[66:67], 0
	v_mov_b64_e32 v[68:69], 0
	v_mov_b64_e32 v[70:71], 0
	v_mov_b64_e32 v[72:73], 0
	v_mov_b64_e32 v[82:83], 0
	v_mov_b64_e32 v[84:85], 0
	v_mov_b64_e32 v[86:87], 0
	v_mov_b64_e32 v[88:89], 0
	v_mov_b64_e32 v[98:99], 0
	v_mov_b64_e32 v[100:101], 0
	v_mov_b64_e32 v[102:103], 0
	v_mov_b64_e32 v[104:105], 0
	v_mov_b64_e32 v[114:115], 0
	v_mov_b64_e32 v[116:117], 0
	v_mov_b64_e32 v[118:119], 0
	v_mov_b64_e32 v[120:121], 0
	v_mov_b64_e32 v[74:75], 0
	v_mov_b64_e32 v[76:77], 0
	v_mov_b64_e32 v[78:79], 0
	v_mov_b64_e32 v[80:81], 0
	v_mov_b64_e32 v[90:91], 0
	v_mov_b64_e32 v[92:93], 0
	v_mov_b64_e32 v[94:95], 0
	v_mov_b64_e32 v[96:97], 0
	v_mov_b64_e32 v[106:107], 0
	v_mov_b64_e32 v[108:109], 0
	v_mov_b64_e32 v[110:111], 0
	v_mov_b64_e32 v[112:113], 0
	v_mov_b64_e32 v[122:123], 0
	v_mov_b64_e32 v[124:125], 0
	v_mov_b64_e32 v[126:127], 0
	v_mov_b64_e32 v[128:129], 0
	.p2alignl 6, 3212836864

; #define WAIT_BAR(N) asm volatile("s_waitcnt vmcnt(" #N ") lgkmcnt(0)\n\ts_barrier":::"memory")
;   #define DMA_K(t,slot) glds16(ksrc+(long)(t)*KVBLK*DMI,(unsigned)__builtin_amdgcn_readfirstlane(kdst+(slot)))
;   #define DMA_V(t,slot) glds16(vsrc+(long)(t)*KVBLK*DMI,(unsigned)__builtin_amdgcn_readfirstlane(vdst+(slot)))
;   #define BIASADD(P0,P1,t) do{ if(BIAS){ const lds_fptr bp_=biasl+KVBLK*(t); _Pragma("unroll") for(int i_=0;i_<4;++i_){ \
;       const f32x4_t b0_=*(const __attribute__((address_space(3))) f32x4_t*)(bp_+8*i_), b1_=*(const __attribute__((address_space(3))) f32x4_t*)(bp_+32+8*i_); \
;       _Pragma("unroll") for(int j_=0;j_<4;++j_){ P0[4*i_+j_]+=b0_[j_]; P1[4*i_+j_]+=b1_[j_]; } } } }while(0)
;   #define CMASK(P0,P1,t) do{int jb_=(t)-(NT-4); if(jb_>=0)cmask(P0,P1,jb_,qrel,hi);}while(0)
;   #define START(P0,P1) do{ const float rm=rowmax(P0,P1); resc=false; \
;     { const float dl=rm; mhat=fadd_s(mhat,dl); \
;       _Pragma("unroll") for(int r=0;r<16;++r){P0[r]=fsub_s(P0[r],dl);P1[r]=fsub_s(P1[r],dl);} \
;       _Pragma("unroll") for(int r=0;r<16;++r)negm[r]=-mhat; asm volatile("":"+v"(negm)); } \
;     _Pragma("unroll") for(int r=0;r<16;++r)P0[r]=__builtin_amdgcn_exp2f(P0[r]); }while(0)
;   #define ROT() do{sl_prev=sl_cur;sl_cur=sl_next;sl_next=(sl_next==(NSLOT-1)*SLOTB)?0:sl_next+SLOTB;}while(0)
;   #define CMASK(P0,P1,t) do{}while(0)
;   #define CMASK(P0,P1,t) do{int jb_=(t)-(NT-4); if(jb_>=0)cmask(P0,P1,jb_,qrel,hi);}while(0)
; #define WAIT_BAR(N) asm volatile("s_waitcnt vmcnt(" #N ") lgkmcnt(0)\n\ts_barrier":::"memory")
;   #define CMASK(P0,P1,t) do{}while(0)
; template<int THRL,bool BIAS> __device__ __forceinline__ void attn_unit(int b,int qb,const bf16*Q,const bf16*__restrict__ K,const bf16*__restrict__ V,bf16*O,const float*__restrict__ biasg,char*shm,const int tid_in){
;     ...
;   f32x16 pA0,pA1,pB0,pB1;
;   int sl_prev=0,sl_cur=0,sl_next=SLOTB;
;     ...
;   DMA_K(2,2*SLOTB);
;   WAIT_BAR(3);
;   qkt(pA0,pA1,Kbase,qr,negm,r32,hi);asm volatile("s_nop 15\n\ts_nop 7":"+v"(pA0),"+v"(pA1));BIASADD(pA0,pA1,0);CMASK(pA0,pA1,0);
;   START(pA0,pA1);
;   _Pragma("unroll") for(int r=0;r<16;++r)pA1[r]=__builtin_amdgcn_exp2f(pA1[r]);
;   WAIT_BAR(0);
;   DMA_K(3,0);DMA_V(1,SLOTB);
;   ROT();
;   kload8(kf,kp0+sl_cur);
;   WAIT_BAR(2);
;   s16x4 vlo[8],vhi[8]; u32x4 pw0,pw1,pw2,pw3;
;     ...
;   int t=1;
;     ...
;   for(;t+5<NT;t+=2){
.LBB0_249:
	v_lshlrev_b32_e32 v0, 1, v42
	v_and_b32_e32 v235, 32, v0
	v_lshrrev_b32_e32 v0, 2, v42
	v_and_or_b32 v0, v0, 3, v221
	v_lshlrev_b32_e32 v222, 6, v0
	v_add_u32_e32 v0, 0, v235
	v_add3_u32 v225, v0, v220, v222
	v_max3_f32 v0, v40, v41, v2
	v_max3_f32 v12, v38, v39, v3
	s_and_b32 s5, s22, 0x3fffffc0
	v_max3_f32 v0, v0, v4, v5
	v_max3_f32 v12, v12, v34, v35
	s_lshl_b32 s5, s5, 2
	v_max3_f32 v0, v0, v36, v37
	v_max3_f32 v12, v12, v8, v9
	s_add_i32 s19, s5, 0
	v_max3_f32 v0, v0, v28, v29
	v_max3_f32 v12, v12, v22, v23
	s_cmp_lg_u32 0, -1
	v_max3_f32 v0, v0, v24, v25
	v_max3_f32 v12, v12, v10, v11
	s_mov_b32 s18, 1
	v_max3_f32 v0, v0, v26, v27
	v_max3_f32 v12, v12, v18, v19
	s_mov_b32 s7, 0
	v_max3_f32 v0, v0, v20, v21
	v_max3_f32 v12, v12, v6, v7
	v_lshl_add_u32 v237, v233, 2, s19
	v_max3_f32 v0, v0, v14, v15
	v_lshl_add_u32 v234, v221, 2, s19
	v_max_f32_e32 v0, v0, v12
	s_nop 0
	v_mov_b32_e32 v12, v0
	s_nop 1
	v_permlane32_swap_b32_e32 v0, v12
	v_max_f32_e32 v0, v0, v12
	s_nop 0
	v_add_f32_e32 v224, v1, v0
	v_sub_f32_e32 v2, v2, v0
	v_sub_f32_e32 v3, v3, v0
	v_sub_f32_e32 v12, v40, v0
	v_sub_f32_e32 v13, v41, v0
	v_sub_f32_e32 v16, v38, v0
	s_nop 0
	v_xor_b32_e32 v48, 0x80000000, v224
	v_mov_b32_e32 v49, v48
	v_mov_b32_e32 v50, v48
	v_mov_b32_e32 v51, v48
	v_mov_b32_e32 v52, v48
	v_mov_b32_e32 v53, v48
	v_mov_b32_e32 v54, v48
	v_mov_b32_e32 v55, v48
	v_mov_b32_e32 v56, v48
	v_mov_b32_e32 v57, v48
	v_mov_b32_e32 v58, v48
	v_mov_b32_e32 v59, v48
	v_mov_b32_e32 v60, v48
	v_mov_b32_e32 v61, v48
	v_mov_b32_e32 v62, v48
	v_mov_b32_e32 v63, v48
	s_waitcnt vmcnt(0) lgkmcnt(0)
	s_barrier
	v_exp_f32_e32 v64, v2
	v_exp_f32_e32 v65, v3
	v_lshl_add_u64 v[2:3], v[212:213], 0, s[50:51]
	s_mov_b32 s5, m0
	s_mov_b32 m0, s38
	s_nop 0
	global_load_lds_dwordx4 v[2:3], off
	s_mov_b32 m0, s5
	s_cselect_b32 s5, 0, 0
	s_add_i32 s4, s5, s4
	v_lshl_add_u64 v[2:3], v[214:215], 0, s[46:47]
	s_add_i32 s4, s4, 0x8000
	s_mov_b32 s5, m0
	s_mov_b32 m0, s4
	s_nop 0
	global_load_lds_dwordx4 v[2:3], off
	s_mov_b32 m0, s5
	ds_read_b128 v[188:191], v238 offset:8192
	ds_read_b128 v[184:187], v238 offset:8704
	ds_read_b128 v[180:183], v238 offset:10240
	ds_read_b128 v[176:179], v238 offset:10752
	ds_read_b128 v[172:175], v238 offset:12288
	ds_read_b128 v[168:171], v238 offset:12800
	ds_read_b128 v[164:167], v238 offset:14336
	ds_read_b128 v[160:163], v238 offset:14848
	v_sub_f32_e32 v4, v4, v0
	v_sub_f32_e32 v17, v39, v0
	v_sub_f32_e32 v5, v5, v0
	v_sub_f32_e32 v30, v36, v0
	v_sub_f32_e32 v28, v28, v0
	v_sub_f32_e32 v31, v37, v0
	v_sub_f32_e32 v29, v29, v0
	v_sub_f32_e32 v32, v34, v0
	v_sub_f32_e32 v8, v8, v0
	v_sub_f32_e32 v33, v35, v0
	v_sub_f32_e32 v9, v9, v0
	v_sub_f32_e32 v24, v24, v0
	v_sub_f32_e32 v26, v26, v0
	v_sub_f32_e32 v25, v25, v0
	v_sub_f32_e32 v27, v27, v0
	v_sub_f32_e32 v22, v22, v0
	v_sub_f32_e32 v10, v10, v0
	v_sub_f32_e32 v23, v23, v0
	v_sub_f32_e32 v11, v11, v0
	v_sub_f32_e32 v20, v20, v0
	v_sub_f32_e32 v14, v14, v0
	v_sub_f32_e32 v21, v21, v0
	v_sub_f32_e32 v15, v15, v0
	v_sub_f32_e32 v18, v18, v0
	v_sub_f32_e32 v6, v6, v0
	v_sub_f32_e32 v19, v19, v0
	v_sub_f32_e32 v0, v7, v0
	v_exp_f32_e32 v80, v12
	v_exp_f32_e32 v81, v13
	v_exp_f32_e32 v82, v16
	v_exp_f32_e32 v83, v17
	v_exp_f32_e32 v84, v30
	v_exp_f32_e32 v85, v31
	v_exp_f32_e32 v86, v32
	v_exp_f32_e32 v87, v33
	v_exp_f32_e32 v88, v24
	v_exp_f32_e32 v89, v25
	v_exp_f32_e32 v90, v22
	v_exp_f32_e32 v91, v23
	v_exp_f32_e32 v92, v20
	v_exp_f32_e32 v93, v21
	v_exp_f32_e32 v94, v18
	v_exp_f32_e32 v95, v19
	v_exp_f32_e32 v66, v4
	v_exp_f32_e32 v67, v5
	v_exp_f32_e32 v68, v28
	v_exp_f32_e32 v69, v29
	v_exp_f32_e32 v70, v8
	v_exp_f32_e32 v71, v9
	v_exp_f32_e32 v72, v26
	v_exp_f32_e32 v73, v27
	v_exp_f32_e32 v74, v10
	v_exp_f32_e32 v75, v11
	v_exp_f32_e32 v76, v14
	v_exp_f32_e32 v77, v15
	v_exp_f32_e32 v78, v6
	v_exp_f32_e32 v79, v0
	s_waitcnt vmcnt(2) lgkmcnt(0)
	s_barrier
	s_cmp_lt_i32 s35, 7
	v_cmp_gt_u32_e64 s[4:5], 32, v231
	s_cbranch_scc1 .LBB0_265
	v_mov_b32_e32 v14, v1
	v_mov_b32_e32 v15, v1
	v_readlane_b32 s7, v255, 10
	v_mov_b32_e32 v0, v1
	v_mov_b32_e32 v2, v1
	v_mov_b32_e32 v3, v1
	v_mov_b32_e32 v4, v1
	v_mov_b32_e32 v5, v1
	v_mov_b32_e32 v6, v1
	v_mov_b32_e32 v7, v1
	v_mov_b32_e32 v8, v1
	v_mov_b32_e32 v9, v1
	v_mov_b32_e32 v10, v1
	v_mov_b32_e32 v11, v1
	v_mov_b32_e32 v12, v1
	v_mov_b32_e32 v13, v1
	v_mov_b64_e32 v[46:47], v[14:15]
	v_mov_b64_e32 v[30:31], v[14:15]
	v_lshl_add_u64 v[200:201], v[214:215], 0, s[50:51]
	v_lshl_add_u64 v[202:203], v[212:213], 0, s[52:53]
	v_lshl_add_u32 v204, v239, 4, s7
	s_mov_b32 s18, 0
	s_movk_i32 s7, 0x4000
	s_movk_i32 s69, 0x2000
	v_mov_b32_e32 v230, 0
	s_mov_b32 s68, 6
	v_mov_b64_e32 v[44:45], v[12:13]
	v_mov_b64_e32 v[42:43], v[10:11]
	v_mov_b64_e32 v[40:41], v[8:9]
	v_mov_b64_e32 v[38:39], v[6:7]
	v_mov_b64_e32 v[36:37], v[4:5]
	v_mov_b64_e32 v[34:35], v[2:3]
	v_mov_b64_e32 v[32:33], v[0:1]
	v_mov_b64_e32 v[28:29], v[12:13]
	v_mov_b64_e32 v[26:27], v[10:11]
	v_mov_b64_e32 v[24:25], v[8:9]
	v_mov_b64_e32 v[22:23], v[6:7]
	v_mov_b64_e32 v[20:21], v[4:5]
	v_mov_b64_e32 v[18:19], v[2:3]
	v_mov_b64_e32 v[16:17], v[0:1]
	.p2alignl 6, 3212836864

; #define WAIT_BAR(N) asm volatile("s_waitcnt vmcnt(" #N ") lgkmcnt(0)\n\ts_barrier":::"memory")
;   #define DMA_K(t,slot) glds16(ksrc+(long)(t)*KVBLK*DMI,(unsigned)__builtin_amdgcn_readfirstlane(kdst+(slot)))
;   #define DMA_V(t,slot) glds16(vsrc+(long)(t)*KVBLK*DMI,(unsigned)__builtin_amdgcn_readfirstlane(vdst+(slot)))
;   #define BIASADD(P0,P1,t) do{ if(BIAS){ const lds_fptr bp_=biasl+KVBLK*(t); _Pragma("unroll") for(int i_=0;i_<4;++i_){ \
;       const f32x4_t b0_=*(const __attribute__((address_space(3))) f32x4_t*)(bp_+8*i_), b1_=*(const __attribute__((address_space(3))) f32x4_t*)(bp_+32+8*i_); \
;       _Pragma("unroll") for(int j_=0;j_<4;++j_){ P0[4*i_+j_]+=b0_[j_]; P1[4*i_+j_]+=b1_[j_]; } } } }while(0)
;   #define CMASK(P0,P1,t) do{int jb_=(t)-(NT-4); if(jb_>=0)cmask(P0,P1,jb_,qrel,hi);}while(0)
;   #define START(P0,P1) do{ const float rm=rowmax(P0,P1); resc=false; \
;     { const float dl=rm; mhat=fadd_s(mhat,dl); \
;       _Pragma("unroll") for(int r=0;r<16;++r){P0[r]=fsub_s(P0[r],dl);P1[r]=fsub_s(P1[r],dl);} \
;       _Pragma("unroll") for(int r=0;r<16;++r)negm[r]=-mhat; asm volatile("":"+v"(negm)); } \
;     _Pragma("unroll") for(int r=0;r<16;++r)P0[r]=__builtin_amdgcn_exp2f(P0[r]); }while(0)
;   #define ROT() do{sl_prev=sl_cur;sl_cur=sl_next;sl_next=(sl_next==(NSLOT-1)*SLOTB)?0:sl_next+SLOTB;}while(0)
;   #define CMASK(P0,P1,t) do{}while(0)
;   #define CMASK(P0,P1,t) do{int jb_=(t)-(NT-4); if(jb_>=0)cmask(P0,P1,jb_,qrel,hi);}while(0)
;   #define CMASK(P0,P1,t) do{int jb_=(t)-(NT-4); if(jb_>=0)cmask(P0,P1,jb_,qrel,hi);}while(0)
; template<int THRL,bool BIAS> __device__ __forceinline__ void attn_unit(int b,int qb,const bf16*Q,const bf16*__restrict__ K,const bf16*__restrict__ V,bf16*O,const float*__restrict__ biasg,char*shm,const int tid_in,const bool comb,const bf16*O0,const float lam,const float osc,const float*__restrict__ ...
;     ...
;   f32x16 pA0,pA1,pB0,pB1;
;   int sl_prev=0,sl_cur=0,sl_next=SLOTB;
;     ...
;   DMA_K(2,2*SLOTB);
;   WAIT_BAR(3);
;   qkt(pA0,pA1,Kbase,qr,negm,r32,hi);asm volatile("s_nop 15\n\ts_nop 7":"+v"(pA0),"+v"(pA1));BIASADD(pA0,pA1,0);CMASK(pA0,pA1,0);
;   START(pA0,pA1);
;   _Pragma("unroll") for(int r=0;r<16;++r)pA1[r]=__builtin_amdgcn_exp2f(pA1[r]);
;   WAIT_BAR(0);
;   DMA_K(3,0);DMA_V(1,SLOTB);
;   ROT();
;   kload8(kf,kp0+sl_cur);
;   WAIT_BAR(3);
;   s16x4 vlo[3],vhi[3]; u32x4 pw0,pw1,pw2,pw3;
;     ...
;   int t=1;
;     ...
;   for(;t+5<NT;t+=2){
.LBB0_278:
	v_lshlrev_b32_e32 v0, 1, v34
	v_and_b32_e32 v248, 32, v0
	v_lshlrev_b32_e32 v0, 4, v34
	v_and_b32_e32 v0, 0xc0, v0
	v_lshl_or_b32 v240, v232, 8, v0
	v_add_u32_e32 v0, 0, v248
	v_add3_u32 v245, v0, v242, v240
	v_max3_f32 v0, v18, v19, v2
	v_max3_f32 v34, v20, v21, v3
	s_and_b32 s5, s5, 0x3fffffc0
	v_max3_f32 v0, v0, v4, v5
	v_max3_f32 v34, v34, v24, v25
	s_lshl_b32 s5, s5, 2
	v_max3_f32 v0, v0, v22, v23
	v_max3_f32 v34, v34, v8, v9
	s_add_i32 s62, s5, 0
	v_max3_f32 v0, v0, v6, v7
	v_max3_f32 v34, v34, v28, v29
	s_add_i32 s62, s62, 0x12000
	v_max3_f32 v0, v0, v26, v27
	v_max3_f32 v34, v34, v12, v13
	s_cmp_lg_u32 0, -1
	v_max3_f32 v0, v0, v10, v11
	v_max3_f32 v34, v34, v32, v33
	s_mov_b32 s6, 1
	v_max3_f32 v0, v0, v30, v31
	v_max3_f32 v34, v34, v16, v17
	s_mov_b32 s76, 0
	v_max3_f32 v0, v0, v14, v15
	v_lshlrev_b32_e32 v230, 4, v232
	v_max_f32_e32 v0, v0, v34
	v_lshl_add_u32 v241, v252, 2, s62
	v_mov_b32_e32 v34, v0
	s_nop 1
	v_permlane32_swap_b32_e32 v0, v34
	v_max_f32_e32 v0, v0, v34
	s_nop 0
	v_add_f32_e32 v224, v1, v0
	v_sub_f32_e32 v2, v2, v0
	v_sub_f32_e32 v3, v3, v0
	v_sub_f32_e32 v18, v18, v0
	v_sub_f32_e32 v19, v19, v0
	v_sub_f32_e32 v20, v20, v0
	s_nop 0
	v_xor_b32_e32 v80, 0x80000000, v224
	v_mov_b32_e32 v81, v80
	v_mov_b32_e32 v82, v80
	v_mov_b32_e32 v83, v80
	v_mov_b32_e32 v84, v80
	v_mov_b32_e32 v85, v80
	v_mov_b32_e32 v86, v80
	v_mov_b32_e32 v87, v80
	v_mov_b32_e32 v88, v80
	v_mov_b32_e32 v89, v80
	v_mov_b32_e32 v90, v80
	v_mov_b32_e32 v91, v80
	v_mov_b32_e32 v92, v80
	v_mov_b32_e32 v93, v80
	v_mov_b32_e32 v94, v80
	v_mov_b32_e32 v95, v80
	s_waitcnt vmcnt(0) lgkmcnt(0)
	s_barrier
	v_exp_f32_e32 v96, v2
	v_exp_f32_e32 v97, v3
	v_lshl_add_u64 v[2:3], v[234:235], 0, s[50:51]
	s_mov_b32 s5, m0
	s_mov_b32 m0, s64
	s_nop 0
	global_load_lds_dwordx4 v[2:3], off
	s_mov_b32 m0, s5
	s_cselect_b32 s5, 0, 0
	s_add_i32 s7, s5, s4
	v_lshl_add_u64 v[2:3], v[236:237], 0, s[46:47]
	s_add_i32 s4, s7, 0xa000
	s_mov_b32 s5, m0
	s_mov_b32 m0, s4
	s_nop 0
	global_load_lds_dwordx4 v[2:3], off
	s_mov_b32 m0, s5
	s_mov_b64 s[4:5], 0x60080
	v_lshl_add_u64 v[2:3], v[236:237], 0, s[4:5]
	s_add_i32 s7, s7, 0xc000
	s_mov_b32 s4, m0
	s_mov_b32 m0, s7
	s_nop 0
	global_load_lds_dwordx4 v[2:3], off
	s_mov_b32 m0, s4
	ds_read_b128 v[220:223], v225 offset:8192
	ds_read_b128 v[212:215], v225 offset:8704
	ds_read_b128 v[216:219], v225 offset:10240
	ds_read_b128 v[204:207], v225 offset:10752
	ds_read_b128 v[208:211], v225 offset:12288
	ds_read_b128 v[200:203], v225 offset:12800
	ds_read_b128 v[196:199], v225 offset:14336
	ds_read_b128 v[192:195], v225 offset:14848
	v_sub_f32_e32 v4, v4, v0
	v_sub_f32_e32 v21, v21, v0
	v_sub_f32_e32 v5, v5, v0
	v_sub_f32_e32 v22, v22, v0
	v_sub_f32_e32 v6, v6, v0
	v_sub_f32_e32 v23, v23, v0
	v_sub_f32_e32 v7, v7, v0
	v_sub_f32_e32 v24, v24, v0
	v_sub_f32_e32 v8, v8, v0
	v_sub_f32_e32 v25, v25, v0
	v_sub_f32_e32 v9, v9, v0
	v_sub_f32_e32 v26, v26, v0
	v_sub_f32_e32 v10, v10, v0
	v_sub_f32_e32 v27, v27, v0
	v_sub_f32_e32 v11, v11, v0
	v_sub_f32_e32 v28, v28, v0
	v_sub_f32_e32 v12, v12, v0
	v_sub_f32_e32 v29, v29, v0
	v_sub_f32_e32 v13, v13, v0
	v_sub_f32_e32 v30, v30, v0
	v_sub_f32_e32 v14, v14, v0
	v_sub_f32_e32 v31, v31, v0
	v_sub_f32_e32 v15, v15, v0
	v_sub_f32_e32 v32, v32, v0
	v_sub_f32_e32 v16, v16, v0
	v_sub_f32_e32 v33, v33, v0
	v_sub_f32_e32 v0, v17, v0
	v_exp_f32_e32 v112, v18
	v_exp_f32_e32 v113, v19
	v_exp_f32_e32 v114, v20
	v_exp_f32_e32 v115, v21
	v_exp_f32_e32 v116, v22
	v_exp_f32_e32 v117, v23
	v_exp_f32_e32 v118, v24
	v_exp_f32_e32 v119, v25
	v_exp_f32_e32 v120, v26
	v_exp_f32_e32 v121, v27
	v_exp_f32_e32 v122, v28
	v_exp_f32_e32 v123, v29
	v_exp_f32_e32 v124, v30
	v_exp_f32_e32 v125, v31
	v_exp_f32_e32 v126, v32
	v_exp_f32_e32 v127, v33
	v_exp_f32_e32 v98, v4
	v_exp_f32_e32 v99, v5
	v_exp_f32_e32 v100, v6
	v_exp_f32_e32 v101, v7
	v_exp_f32_e32 v102, v8
	v_exp_f32_e32 v103, v9
	v_exp_f32_e32 v104, v10
	v_exp_f32_e32 v105, v11
	v_exp_f32_e32 v106, v12
	v_exp_f32_e32 v107, v13
	v_exp_f32_e32 v108, v14
	v_exp_f32_e32 v109, v15
	v_exp_f32_e32 v110, v16
	v_exp_f32_e32 v111, v0
	s_waitcnt vmcnt(3) lgkmcnt(0)
	s_barrier
	s_andn2_b64 vcc, exec, s[22:23]
	v_cmp_gt_u32_e64 s[4:5], 32, v253
	s_cbranch_vccnz .LBB0_294
	v_mov_b32_e32 v14, v1
	v_mov_b32_e32 v15, v1
	v_mov_b32_e32 v0, v1
	v_mov_b32_e32 v2, v1
	v_mov_b32_e32 v3, v1
	v_mov_b32_e32 v4, v1
	v_mov_b32_e32 v5, v1
	v_mov_b32_e32 v6, v1
	v_mov_b32_e32 v7, v1
	v_mov_b32_e32 v8, v1
	v_mov_b32_e32 v9, v1
	v_mov_b32_e32 v10, v1
	v_mov_b32_e32 v11, v1
	v_mov_b32_e32 v12, v1
	v_mov_b32_e32 v13, v1
	v_mov_b64_e32 v[78:79], v[14:15]
	v_mov_b64_e32 v[62:63], v[14:15]
	v_mov_b64_e32 v[46:47], v[14:15]
	v_mov_b64_e32 v[30:31], v[14:15]
	s_mov_b32 s72, 0
	s_movk_i32 s76, 0x4000
	s_movk_i32 s78, 0x2000
	v_mov_b32_e32 v231, 0
	s_mov_b32 s77, 6
	s_mov_b64 s[6:7], 0
	v_mov_b64_e32 v[76:77], v[12:13]
	v_mov_b64_e32 v[74:75], v[10:11]
	v_mov_b64_e32 v[72:73], v[8:9]
	v_mov_b64_e32 v[70:71], v[6:7]
	v_mov_b64_e32 v[68:69], v[4:5]
	v_mov_b64_e32 v[66:67], v[2:3]
	v_mov_b64_e32 v[64:65], v[0:1]
	v_mov_b64_e32 v[60:61], v[12:13]
	v_mov_b64_e32 v[58:59], v[10:11]
	v_mov_b64_e32 v[56:57], v[8:9]
	v_mov_b64_e32 v[54:55], v[6:7]
	v_mov_b64_e32 v[52:53], v[4:5]
	v_mov_b64_e32 v[50:51], v[2:3]
	v_mov_b64_e32 v[48:49], v[0:1]
	v_mov_b64_e32 v[44:45], v[12:13]
	v_mov_b64_e32 v[42:43], v[10:11]
	v_mov_b64_e32 v[40:41], v[8:9]
	v_mov_b64_e32 v[38:39], v[6:7]
	v_mov_b64_e32 v[36:37], v[4:5]
	v_mov_b64_e32 v[34:35], v[2:3]
	v_mov_b64_e32 v[32:33], v[0:1]
	v_mov_b64_e32 v[28:29], v[12:13]
	v_mov_b64_e32 v[26:27], v[10:11]
	v_mov_b64_e32 v[24:25], v[8:9]
	v_mov_b64_e32 v[22:23], v[6:7]
	v_mov_b64_e32 v[20:21], v[4:5]
	v_mov_b64_e32 v[18:19], v[2:3]
	v_mov_b64_e32 v[16:17], v[0:1]
	.p2alignl 6, 3212836864

; template <class Epi, class Sched, bool ALIGN_EPI = false, bool SP2 = false>
; __device__ __forceinline__ void gemm_phase(PG8_LAS unsigned char* lds, const Gemm g, const Sched& S, const Epi& E, const int tid_in) {
;     ...
;         float rsv[8]; E.pre(cur, wr, fr, rsv);
;         const bool has_next = S.next(ui + 1, nxt);
;         const char* nA = has_next ? (const char*)g.A + (size_t)nxt.pm * tstep : cA; const char* nB = has_next ? (const char*)g.Bt + (size_t)nxt.pn * tstep : cB;
;         for (int t = 0; t < nt; t += 2) {
;             const bool last = (t == nt - 2);
;             const char* a1 = cA + (size_t)(t + 1) * kstep;
;             const char* a2 = last ? nA : cA + (size_t)(t + 2) * kstep; const char* b2 = last ? nB : cB + (size_t)(t + 2) * kstep;
;             const char* a3 = a2 + kstep; const char* b3 = b2 + kstep;
;             if (last && has_next) S.a_ready(nxt);
;     ...
; #pragma unroll
;         for (int a = 0; a < 2; ++a)
; #pragma unroll
;             for (int b = 0; b < 2; ++b)
; #pragma unroll
;                 for (int m = 0; m < 4; ++m)
; #pragma unroll
;                     for (int n = 0; n < 2; ++n) acc[a][b][m][n] = (f32x4){0.f, 0.f, 0.f, 0.f};
;         cur = nxt; cA = nA; cB = nB; ++ui;
.LBB0_484:
	s_ashr_i32 s15, s14, 31
	s_lshl_b64 s[18:19], s[14:15], 19
	s_add_u32 s18, s2, s18
	s_addc_u32 s19, s3, s19
	s_and_b64 s[22:23], s[4:5], exec
	s_cselect_b32 s15, s19, s69
	s_cselect_b32 s42, s18, s68
	s_ashr_i32 s13, s12, 31
	s_lshl_b64 s[22:23], s[12:13], 19
	s_add_u32 s22, s20, s22
	s_addc_u32 s23, s21, s23
	s_and_b64 s[58:59], s[4:5], exec
	s_cselect_b32 s13, s23, s71
	s_cselect_b32 s43, s22, s70
	s_add_u32 s68, s68, 0x40080
	s_addc_u32 s69, s69, 0
	s_add_u32 s58, s70, 0x100
	v_mov_b32_e32 v2, 0
	s_addc_u32 s59, s71, 0
	s_mov_b32 s60, -2
	v_mov_b32_e32 v3, v2
	v_mov_b64_e32 v[4:5], 0
	v_mov_b64_e32 v[6:7], 0
	v_mov_b64_e32 v[8:9], 0
	v_mov_b64_e32 v[10:11], 0
	v_mov_b64_e32 v[12:13], 0
	v_mov_b64_e32 v[18:19], 0
	v_mov_b64_e32 v[20:21], 0
	v_mov_b64_e32 v[26:27], 0
	v_mov_b64_e32 v[28:29], 0
	v_mov_b64_e32 v[34:35], 0
	v_mov_b64_e32 v[36:37], 0
	v_mov_b64_e32 v[42:43], 0
	v_mov_b64_e32 v[44:45], 0
	v_mov_b64_e32 v[50:51], 0
	v_mov_b64_e32 v[52:53], 0
	v_mov_b64_e32 v[14:15], 0
	v_mov_b64_e32 v[16:17], 0
	v_mov_b64_e32 v[22:23], 0
	v_mov_b64_e32 v[24:25], 0
	v_mov_b64_e32 v[30:31], 0
	v_mov_b64_e32 v[32:33], 0
	v_mov_b64_e32 v[38:39], 0
	v_mov_b64_e32 v[40:41], 0
	v_mov_b64_e32 v[46:47], 0
	v_mov_b64_e32 v[48:49], 0
	v_mov_b64_e32 v[54:55], 0
	v_mov_b64_e32 v[56:57], 0
	v_mov_b64_e32 v[58:59], 0
	v_mov_b64_e32 v[60:61], 0
	v_mov_b64_e32 v[62:63], 0
	v_mov_b64_e32 v[64:65], 0
	v_mov_b64_e32 v[66:67], 0
	v_mov_b64_e32 v[68:69], 0
	v_mov_b64_e32 v[70:71], 0
	v_mov_b64_e32 v[72:73], 0
	v_mov_b64_e32 v[74:75], 0
	v_mov_b64_e32 v[76:77], 0
	v_mov_b64_e32 v[82:83], 0
	v_mov_b64_e32 v[84:85], 0
	v_mov_b64_e32 v[90:91], 0
	v_mov_b64_e32 v[92:93], 0
	v_mov_b64_e32 v[98:99], 0
	v_mov_b64_e32 v[100:101], 0
	v_mov_b64_e32 v[106:107], 0
	v_mov_b64_e32 v[108:109], 0
	v_mov_b64_e32 v[114:115], 0
	v_mov_b64_e32 v[116:117], 0
	v_mov_b64_e32 v[78:79], 0
	v_mov_b64_e32 v[80:81], 0
	v_mov_b64_e32 v[86:87], 0
	v_mov_b64_e32 v[88:89], 0
	v_mov_b64_e32 v[94:95], 0
	v_mov_b64_e32 v[96:97], 0
	v_mov_b64_e32 v[102:103], 0
	v_mov_b64_e32 v[104:105], 0
	v_mov_b64_e32 v[110:111], 0
	v_mov_b64_e32 v[112:113], 0
	v_mov_b64_e32 v[118:119], 0
	v_mov_b64_e32 v[120:121], 0
	v_mov_b64_e32 v[122:123], 0
	v_mov_b64_e32 v[124:125], 0
	v_mov_b64_e32 v[126:127], 0
	v_mov_b64_e32 v[128:129], 0
	.p2alignl 6, 3212836864

; template <class Epi, class Sched, bool ALIGN_EPI = false, bool SP2 = false>
; __device__ __forceinline__ void gemm_phase(PG8_LAS unsigned char* lds, const Gemm g, const Sched& S, const Epi& E, const int tid_in) {
;     ...
;         float rsv[8]; E.pre(cur, wr, fr, rsv);
;         const bool has_next = S.next(ui + 1, nxt);
;         const char* nA = has_next ? (const char*)g.A + (size_t)nxt.pm * tstep : cA; const char* nB = has_next ? (const char*)g.Bt + (size_t)nxt.pn * tstep : cB;
;         for (int t = 0; t < nt; t += 2) {
;             const bool last = (t == nt - 2);
;             const char* a1 = cA + (size_t)(t + 1) * kstep;
;             const char* a2 = last ? nA : cA + (size_t)(t + 2) * kstep; const char* b2 = last ? nB : cB + (size_t)(t + 2) * kstep;
;             const char* a3 = a2 + kstep; const char* b3 = b2 + kstep;
;             if (last && has_next) S.a_ready(nxt);
;     ...
; #pragma unroll
;         for (int a = 0; a < 2; ++a)
; #pragma unroll
;             for (int b = 0; b < 2; ++b)
; #pragma unroll
;                 for (int m = 0; m < 4; ++m)
; #pragma unroll
;                     for (int n = 0; n < 2; ++n) acc[a][b][m][n] = (f32x4){0.f, 0.f, 0.f, 0.f};
;         cur = nxt; cA = nA; cB = nB; ++ui;
.LBB0_621:
	s_ashr_i32 s7, s6, 31
	s_lshl_b64 s[22:23], s[6:7], 19
	s_add_u32 s22, s1, s22
	s_addc_u32 s23, s2, s23
	s_and_b64 s[58:59], s[4:5], exec
	s_cselect_b32 s7, s23, s71
	s_cselect_b32 s43, s22, s70
	s_ashr_i32 s19, s18, 31
	s_lshl_b64 s[58:59], s[18:19], 19
	s_add_u32 s68, s3, s58
	s_addc_u32 s69, s20, s59
	s_and_b64 s[58:59], s[4:5], exec
	s_cselect_b32 s19, s69, s73
	s_cselect_b32 s58, s68, s72
	s_add_u32 s70, s70, 0x40080
	s_addc_u32 s71, s71, 0
	s_add_u32 s59, s72, 0x100
	v_mov_b32_e32 v2, 0
	s_addc_u32 s60, s73, 0
	s_mov_b32 s61, -2
	v_mov_b32_e32 v3, v2
	v_mov_b64_e32 v[4:5], 0
	v_mov_b64_e32 v[10:11], 0
	v_mov_b64_e32 v[12:13], 0
	v_mov_b64_e32 v[18:19], 0
	v_mov_b64_e32 v[20:21], 0
	v_mov_b64_e32 v[26:27], 0
	v_mov_b64_e32 v[28:29], 0
	v_mov_b64_e32 v[34:35], 0
	v_mov_b64_e32 v[36:37], 0
	v_mov_b64_e32 v[42:43], 0
	v_mov_b64_e32 v[44:45], 0
	v_mov_b64_e32 v[50:51], 0
	v_mov_b64_e32 v[52:53], 0
	v_mov_b64_e32 v[58:59], 0
	v_mov_b64_e32 v[60:61], 0
	v_mov_b64_e32 v[6:7], 0
	v_mov_b64_e32 v[8:9], 0
	v_mov_b64_e32 v[14:15], 0
	v_mov_b64_e32 v[16:17], 0
	v_mov_b64_e32 v[22:23], 0
	v_mov_b64_e32 v[24:25], 0
	v_mov_b64_e32 v[30:31], 0
	v_mov_b64_e32 v[32:33], 0
	v_mov_b64_e32 v[38:39], 0
	v_mov_b64_e32 v[40:41], 0
	v_mov_b64_e32 v[46:47], 0
	v_mov_b64_e32 v[48:49], 0
	v_mov_b64_e32 v[54:55], 0
	v_mov_b64_e32 v[56:57], 0
	v_mov_b64_e32 v[62:63], 0
	v_mov_b64_e32 v[64:65], 0
	v_mov_b64_e32 v[66:67], 0
	v_mov_b64_e32 v[68:69], 0
	v_mov_b64_e32 v[74:75], 0
	v_mov_b64_e32 v[76:77], 0
	v_mov_b64_e32 v[82:83], 0
	v_mov_b64_e32 v[84:85], 0
	v_mov_b64_e32 v[90:91], 0
	v_mov_b64_e32 v[92:93], 0
	v_mov_b64_e32 v[98:99], 0
	v_mov_b64_e32 v[100:101], 0
	v_mov_b64_e32 v[106:107], 0
	v_mov_b64_e32 v[108:109], 0
	v_mov_b64_e32 v[114:115], 0
	v_mov_b64_e32 v[116:117], 0
	v_mov_b64_e32 v[122:123], 0
	v_mov_b64_e32 v[124:125], 0
	v_mov_b64_e32 v[70:71], 0
	v_mov_b64_e32 v[72:73], 0
	v_mov_b64_e32 v[78:79], 0
	v_mov_b64_e32 v[80:81], 0
	v_mov_b64_e32 v[86:87], 0
	v_mov_b64_e32 v[88:89], 0
	v_mov_b64_e32 v[94:95], 0
	v_mov_b64_e32 v[96:97], 0
	v_mov_b64_e32 v[102:103], 0
	v_mov_b64_e32 v[104:105], 0
	v_mov_b64_e32 v[110:111], 0
	v_mov_b64_e32 v[112:113], 0
	v_mov_b64_e32 v[118:119], 0
	v_mov_b64_e32 v[120:121], 0
	v_mov_b64_e32 v[126:127], 0
	v_mov_b64_e32 v[128:129], 0
	.p2alignl 6, 3212836864

; template <class Epi, class Sched, bool ALIGN_EPI = false, bool SP2 = false>
; __device__ __forceinline__ void gemm_phase(PG8_LAS unsigned char* lds, const Gemm g, const Sched& S, const Epi& E, const int tid_in) {
;     ...
;         float rsv[8]; E.pre(cur, wr, fr, rsv);
;         const bool has_next = S.next(ui + 1, nxt);
;         const char* nA = has_next ? (const char*)g.A + (size_t)nxt.pm * tstep : cA; const char* nB = has_next ? (const char*)g.Bt + (size_t)nxt.pn * tstep : cB;
;         for (int t = 0; t < nt; t += 2) {
;             const bool last = (t == nt - 2);
;             const char* a1 = cA + (size_t)(t + 1) * kstep;
;             const char* a2 = last ? nA : cA + (size_t)(t + 2) * kstep; const char* b2 = last ? nB : cB + (size_t)(t + 2) * kstep;
;             const char* a3 = a2 + kstep; const char* b3 = b2 + kstep;
;             if (last && has_next) S.a_ready(nxt);
;     ...
; #pragma unroll
;         for (int a = 0; a < 2; ++a)
; #pragma unroll
;             for (int b = 0; b < 2; ++b)
; #pragma unroll
;                 for (int m = 0; m < 4; ++m)
; #pragma unroll
;                     for (int n = 0; n < 2; ++n) acc[a][b][m][n] = (f32x4){0.f, 0.f, 0.f, 0.f};
;         cur = nxt; cA = nA; cB = nB; ++ui;
.LBB0_702:
	s_add_u32 s62, s20, 0x100
	v_mov_b32_e32 v2, 0
	s_addc_u32 s63, s21, 0
	s_mov_b32 s64, -2
	v_mov_b32_e32 v3, v2
	v_mov_b64_e32 v[4:5], 0
	v_mov_b64_e32 v[6:7], 0
	v_mov_b64_e32 v[8:9], 0
	v_mov_b64_e32 v[10:11], 0
	v_mov_b64_e32 v[12:13], 0
	v_mov_b64_e32 v[18:19], 0
	v_mov_b64_e32 v[20:21], 0
	v_mov_b64_e32 v[26:27], 0
	v_mov_b64_e32 v[28:29], 0
	v_mov_b64_e32 v[34:35], 0
	v_mov_b64_e32 v[36:37], 0
	v_mov_b64_e32 v[42:43], 0
	v_mov_b64_e32 v[44:45], 0
	v_mov_b64_e32 v[50:51], 0
	v_mov_b64_e32 v[52:53], 0
	v_mov_b64_e32 v[14:15], 0
	v_mov_b64_e32 v[16:17], 0
	v_mov_b64_e32 v[22:23], 0
	v_mov_b64_e32 v[24:25], 0
	v_mov_b64_e32 v[30:31], 0
	v_mov_b64_e32 v[32:33], 0
	v_mov_b64_e32 v[38:39], 0
	v_mov_b64_e32 v[40:41], 0
	v_mov_b64_e32 v[46:47], 0
	v_mov_b64_e32 v[48:49], 0
	v_mov_b64_e32 v[54:55], 0
	v_mov_b64_e32 v[56:57], 0
	v_mov_b64_e32 v[58:59], 0
	v_mov_b64_e32 v[60:61], 0
	v_mov_b64_e32 v[62:63], 0
	v_mov_b64_e32 v[64:65], 0
	v_mov_b64_e32 v[66:67], 0
	v_mov_b64_e32 v[68:69], 0
	v_mov_b64_e32 v[70:71], 0
	v_mov_b64_e32 v[72:73], 0
	v_mov_b64_e32 v[74:75], 0
	v_mov_b64_e32 v[76:77], 0
	v_mov_b64_e32 v[82:83], 0
	v_mov_b64_e32 v[84:85], 0
	v_mov_b64_e32 v[90:91], 0
	v_mov_b64_e32 v[92:93], 0
	v_mov_b64_e32 v[98:99], 0
	v_mov_b64_e32 v[100:101], 0
	v_mov_b64_e32 v[106:107], 0
	v_mov_b64_e32 v[108:109], 0
	v_mov_b64_e32 v[114:115], 0
	v_mov_b64_e32 v[116:117], 0
	v_mov_b64_e32 v[78:79], 0
	v_mov_b64_e32 v[80:81], 0
	v_mov_b64_e32 v[86:87], 0
	v_mov_b64_e32 v[88:89], 0
	v_mov_b64_e32 v[94:95], 0
	v_mov_b64_e32 v[96:97], 0
	v_mov_b64_e32 v[102:103], 0
	v_mov_b64_e32 v[104:105], 0
	v_mov_b64_e32 v[110:111], 0
	v_mov_b64_e32 v[112:113], 0
	v_mov_b64_e32 v[118:119], 0
	v_mov_b64_e32 v[120:121], 0
	v_mov_b64_e32 v[122:123], 0
	v_mov_b64_e32 v[124:125], 0
	v_mov_b64_e32 v[126:127], 0
	v_mov_b64_e32 v[128:129], 0
	.p2alignl 6, 3212836864
